# combo k=2 + phase B items-first for WGs with (bid>>3)&1
# speedup vs baseline: 1.0160x; 1.0039x over previous
; __global__ void __launch_bounds__(256, 2) hybrid_megakernel(Params p) {
;     ...
;     for (int vb = bid; vb < 512; vb += nb) {
;       { const int q2 = vb >> 3; inproj_tile<4>(p, l, (vb & 7) * 16 + (q2 & 15), 8 + (q2 >> 4), lds); }
;       if (vb < 64) cmp_item(p, l, vb, lds);
;       else {
;         const int j = vb - 64;
;         if (vb >= 256) { const int i2 = (vb - 256) >> 3; inproj_tile<2>(p, l, (vb & 7) * 16 + (i2 & 15), 24 + (i2 >> 4), lds); }
;         win_item(p, j, lds);
;         if (j + 448 < 512) win_item(p, j + 448, lds);
;         for (int it = j; it < 1536; it += 448) dil_item(p, it, lds);
;       }
;     }
.LBB0_213:
	s_or_b64 exec, exec, s[0:1]
	v_readlane_b32 s0, v235, 23
	v_readlane_b32 s1, v235, 24
	s_andn2_b64 vcc, exec, s[0:1]
	s_waitcnt lgkmcnt(0)
	v_cndmask_b32_e64 v0, 0, 1, s[0:1]
	v_cmp_ne_u32_e64 s[2:3], 1, v0
	s_barrier
	s_nop 0
	v_writelane_b32 v234, s2, 27
	s_nop 1
	v_writelane_b32 v234, s3, 28
	s_cbranch_vccnz .LBB0_298
	v_readlane_b32 s0, v234, 24
	s_mul_i32 s28, s0, 0xd00
	s_lshl_b32 s29, s0, 1
	v_readlane_b32 s30, v234, 18
	v_readlane_b32 s31, v234, 17
	v_readlane_b32 s34, v234, 14
	v_readlane_b32 s35, v234, 13
	v_readlane_b32 s36, v235, 0
	s_nop 1
	s_lshr_b32 s98, s36, 3
	s_and_b32 s98, s98, 1
	s_branch .LBB0_217
